# DA loop: LDS-DMA m0 targets formed inside PV gaps, exposed DMA blocks 7 instructions each (pre-advanced scalar bases)
# baseline (speedup 1.0000x reference)
; __device__ __forceinline__ void da_phase(LAS unsigned char* lds, const bf16* Q, const bf16* Kb, const bf16* Vb, bf16* O, const float* lq1, const float* lk1, const float* lq2, const float* lk2,
;                                          const float* t5, int G, int wave, int lane, int tid) {
;     ...
;         const char* kub = (const char*)Kb + (((size_t)h * T + tok0 + 32 * (wave & 1)) * 128 + (wave >> 2) * 64 + ((wave >> 1) & 1) * 32) * 2;
;         const char* vub = (const char*)Vb + (((size_t)h * T + tok0 + 16 * ((2 * wave) & 3)) * 128 + ((2 * wave) >> 2) * 32) * 2;
;         const unsigned kofs = (unsigned)(((lane >> 2) * 128 + ((lane & 3) ^ ((lane >> 4) & 3)) * 8) * 2);
;         const unsigned vofs = (unsigned)(((lane >> 2) * 128 + (lane & 3) * 8) * 2);
.LBB0_201:
	s_lshl_b32 s18, s38, 7
	v_readlane_b32 s0, v254, 47
	s_or_b32 s38, s18, s0
	s_mul_i32 s10, s36, 0x18000
	s_add_u32 s0, s10, s38
	s_addc_u32 s1, 0, 0
	s_add_u32 s0, s0, s14
	s_addc_u32 s1, s1, s15
	v_lshl_add_u64 v[2:3], s[0:1], 0, v[188:189]
	v_readlane_b32 s0, v254, 20
	s_add_u32 s0, s14, s0
	s_addc_u32 s1, s15, 0
	s_add_u32 s0, s0, s10
	s_addc_u32 s1, s1, 0
	s_lshl_b64 s[0:1], s[0:1], 8
	v_lshlrev_b64 v[2:3], 8, v[2:3]
	s_add_u32 s10, s34, s0
	v_lshl_add_u64 v[2:3], v[192:193], 0, v[2:3]
	s_addc_u32 s11, s35, s1
	s_mov_b32 m0, s3
	global_load_dwordx4 v[120:123], v[2:3], off
	global_load_dwordx4 v[124:127], v[2:3], off offset:32
	global_load_dwordx4 v[128:131], v[2:3], off offset:64
	global_load_dwordx4 v[132:135], v[2:3], off offset:96
	s_add_u32 s16, s30, s0
	v_lshl_add_u64 v[2:3], s[10:11], 0, v[194:195]
	s_addc_u32 s17, s31, s1
	global_load_lds_dwordx4 v[2:3], off
	v_lshl_add_u64 v[4:5], v[2:3], 0, s[62:63]
	s_add_i32 m0, s3, 0x400
	s_mov_b64 s[10:11], 0x4000
	global_load_lds_dwordx4 v[4:5], off
	v_lshl_add_u64 v[4:5], s[16:17], 0, v[196:197]
	s_add_i32 m0, s3, 0xc000
	v_lshl_add_u64 v[6:7], v[4:5], 0, s[62:63]
	global_load_lds_dwordx4 v[4:5], off
	s_add_i32 m0, s3, 0xc400
	s_mov_b64 s[16:17], 0x5000
	global_load_lds_dwordx4 v[6:7], off
	v_lshl_add_u64 v[6:7], v[2:3], 0, s[10:11]
	s_add_i32 m0, s3, 0x4000
	v_lshl_add_u64 v[2:3], v[2:3], 0, s[16:17]
	global_load_lds_dwordx4 v[6:7], off
	s_add_i32 m0, s3, 0x4400
	v_add_u32_e32 v0, s18, v228
	global_load_lds_dwordx4 v[2:3], off
	v_lshl_add_u64 v[2:3], v[4:5], 0, s[10:11]
	s_add_i32 s10, 0, 0x10000
	v_readlane_b32 s11, v254, 22
	s_add_i32 m0, s10, s11
	v_readlane_b32 s11, v254, 23
	v_lshl_add_u64 v[2:3], v[4:5], 0, s[16:17]
	s_add_i32 m0, s10, s11
	v_mov_b32_e32 v14, v1
	v_mov_b32_e32 v15, v1
	v_lshl_add_u64 v[202:203], v[198:199], 0, s[0:1]
	v_lshl_add_u64 v[204:205], v[200:201], 0, s[0:1]
	v_sub_u32_e32 v231, v219, v0
	v_readlane_b32 s0, v254, 48
	v_mov_b32_e32 v0, v1
	v_mov_b32_e32 v2, v1
	v_mov_b32_e32 v3, v1
	v_mov_b32_e32 v4, v1
	v_mov_b32_e32 v5, v1
	v_mov_b32_e32 v6, v1
	v_mov_b32_e32 v7, v1
	v_mov_b32_e32 v8, v1
	v_mov_b32_e32 v9, v1
	v_mov_b32_e32 v10, v1
	v_mov_b32_e32 v11, v1
	v_mov_b32_e32 v12, v1
	v_mov_b32_e32 v13, v1
	v_mov_b64_e32 v[30:31], v[14:15]
	v_mov_b64_e32 v[46:47], v[14:15]
	v_mov_b64_e32 v[62:63], v[14:15]
	v_mov_b64_e32 v[78:79], v[14:15]
	v_subrev_u32_e32 v230, s18, v227
	s_sub_i32 s40, s0, s18
	s_lshl_b32 s41, s39, 6
	s_mov_b32 s44, 0
	s_mov_b32 s50, -1
	v_mov_b32_e32 v232, 0
	s_mov_b64 s[16:17], 0
	s_mov_b32 s45, 2
	v_mov_b32_e32 v112, 0
	v_mov_b32_e32 v113, 0
	v_mov_b32_e32 v114, 0
	v_mov_b32_e32 v115, 0
	v_mov_b32_e32 v116, 0
	v_mov_b32_e32 v117, 0
	v_mov_b32_e32 v118, 0
	v_mov_b32_e32 v119, 0
	v_mov_b32_e32 v136, 0
	v_mov_b32_e32 v137, 0
	v_mov_b32_e32 v138, 0
	v_mov_b32_e32 v139, 0
	v_mov_b32_e32 v140, 0
	v_mov_b32_e32 v141, 0
	v_mov_b32_e32 v142, 0
	v_mov_b32_e32 v143, 0
	v_mov_b64_e32 v[28:29], v[12:13]
	v_mov_b64_e32 v[26:27], v[10:11]
	v_mov_b64_e32 v[24:25], v[8:9]
	v_mov_b64_e32 v[22:23], v[6:7]
	v_mov_b64_e32 v[20:21], v[4:5]
	v_mov_b64_e32 v[18:19], v[2:3]
	v_mov_b64_e32 v[16:17], v[0:1]
	v_mov_b64_e32 v[44:45], v[12:13]
	v_mov_b64_e32 v[42:43], v[10:11]
	v_mov_b64_e32 v[40:41], v[8:9]
	v_mov_b64_e32 v[38:39], v[6:7]
	v_mov_b64_e32 v[36:37], v[4:5]
	v_mov_b64_e32 v[34:35], v[2:3]
	v_mov_b64_e32 v[32:33], v[0:1]
	v_mov_b64_e32 v[60:61], v[12:13]
	v_mov_b64_e32 v[58:59], v[10:11]
	v_mov_b64_e32 v[56:57], v[8:9]
	v_mov_b64_e32 v[54:55], v[6:7]
	v_mov_b64_e32 v[52:53], v[4:5]
	v_mov_b64_e32 v[50:51], v[2:3]
	v_mov_b64_e32 v[48:49], v[0:1]
	v_mov_b64_e32 v[76:77], v[12:13]
	v_mov_b64_e32 v[74:75], v[10:11]
	v_mov_b64_e32 v[72:73], v[8:9]
	v_mov_b64_e32 v[70:71], v[6:7]
	v_mov_b64_e32 v[68:69], v[4:5]
	v_mov_b64_e32 v[66:67], v[2:3]
	v_mov_b64_e32 v[64:65], v[0:1]
	v_mov_b32_e32 v229, 0
	v_mov_b32_e32 v233, 0
	v_mov_b32_e32 v14, 0
	s_mov_b32 s46, 0
	s_mov_b32 s47, 2
	s_waitcnt vmcnt(0)
	s_barrier
	s_add_i32 s0, s40, s44
	s_cmpk_gt_i32 s0, 0x9e
	s_cselect_b32 s20, 2, 1
	s_cmpk_lt_i32 s0, 0xff42
	s_cselect_b64 s[0:1], -1, 0
	s_cmp_lg_u64 s[0:1], 0
	s_subb_u32 s51, s20, 0
	s_mov_b64 s[0:1], 0x1b208000
	v_lshl_add_u64 v[204:205], v[204:205], 0, s[0:1]
	s_mov_b64 s[0:1], 0x27204000
	v_lshl_add_u64 v[202:203], v[202:203], 0, s[0:1]
	s_nop 0
	v_readfirstlane_b32 s68, v204
	v_readfirstlane_b32 s69, v205
	v_readfirstlane_b32 s74, v202
	v_readfirstlane_b32 s75, v203
	s_nop 3
	s_sub_u32 s68, s68, 0x4000
	s_subb_u32 s69, s69, 0
	s_sub_u32 s74, s74, 0x4000
	s_subb_u32 s75, s75, 0
	s_add_i32 s19, s3, 0x8000
	s_add_i32 s32, s3, 0x10000
	v_add_u32_e32 v204, 0x1000, v194
	v_add_u32_e32 v205, 0x1000, v196
	s_mov_b32 s18, 0xff800000
	s_mov_b32 s21, 0
	v_add_u32_e32 v253, v216, v191
	v_add_u32_e32 v252, v216, v218
	ds_read_b128 v[172:175], v253
	ds_read_b128 v[176:179], v252
	ds_read_b128 v[168:171], v253 offset:4096
	ds_read_b128 v[164:167], v252 offset:4096
	s_waitcnt lgkmcnt(0)
	v_mov_b32_e32 v0, 0
	v_mov_b32_e32 v2, 0
	v_mov_b32_e32 v3, 0
	v_mov_b32_e32 v5, 0
	v_mov_b32_e32 v6, 0
	v_mov_b32_e32 v7, 0
	v_mov_b32_e32 v8, 0
	v_mov_b32_e32 v9, 0
	v_mov_b32_e32 v10, 0
	v_mov_b32_e32 v15, 0
	v_mov_b32_e32 v80, 0
	v_mov_b32_e32 v81, 0
	v_mov_b32_e32 v82, 0
	v_mov_b32_e32 v83, 0
	v_mov_b32_e32 v84, 0
	v_mov_b32_e32 v85, 0
	v_mov_b32_e32 v86, 0
	v_mov_b32_e32 v87, 0
	v_mov_b32_e32 v184, 0
	v_mov_b32_e32 v185, 0
	v_mov_b32_e32 v209, 0
	v_mov_b32_e32 v235, 0
	v_mov_b32_e32 v144, 0
	v_mov_b32_e32 v145, 0
	v_mov_b32_e32 v146, 0
	v_mov_b32_e32 v147, 0
	v_mov_b32_e32 v156, 0
	v_mov_b32_e32 v157, 0
	v_mov_b32_e32 v158, 0
	v_mov_b32_e32 v159, 0
	v_mov_b32_e32 v160, 0
	v_mov_b32_e32 v161, 0
	s_branch .LBB0_204

; #define LGKM_WAIT(n) asm volatile("s_waitcnt lgkmcnt(" #n ")" ::: "memory")
; #define SCHED_FENCE() __builtin_amdgcn_sched_barrier(0)
; #define DA_VREADS(v, vaddr, DB) do { _Pragma("unroll") for (int k_ = 0; k_ < 4; ++k_) { DS_RDTR(v[2 * k_], vaddr, (DB) * 4096 + k_ * 1024); DS_RDTR(v[2 * k_ + 1], vaddr, (DB) * 4096 + k_ * 1024 + 512); } } while (0)
; #define DA_GROUP(v, DB, P, B, acc) do { DA_GAP(v, DB, 0, P, (B), acc); DA_GAP(v, DB, 1, P, (B) + 2, acc); DA_GAP(v, DB, 2, P, (B) + 4, acc); DA_GAP(v, DB, 3, P, (B) + 6, acc); } while (0)
; #define DA_PACK8(P, B) (U4){cvtpk(P[(B)], P[(B) + 1]), cvtpk(P[(B) + 2], P[(B) + 3]), cvtpk(P[(B) + 4], P[(B) + 5]), cvtpk(P[(B) + 6], P[(B) + 7])}
; __device__ __forceinline__ void da_phase(LAS unsigned char* lds, const bf16* Q, const bf16* Kb, const bf16* Vb, bf16* O, const float* lq1, const float* lk1, const float* lq2, const float* lk2,
;                                          const float* t5, int G, int wave, int lane, int tid) {
;     ...
;             float sa = 0.f, sb = 0.f;
;             SCHED_FENCE(); DA_GROUP(va, 0, p0, 0, sa);
;             DA_VREADS(va, vaddr_p, 2); SCHED_FENCE();
;             DA_GROUP(vb, 1, p0, 8, sa);
;             DA_VREADS(vb, vaddr_p, 3); LGKM_WAIT(8); SCHED_FENCE();
;             DA_GROUP(va, 2, p1, 0, sa);
;             LGKM_WAIT(0); SCHED_FENCE();
;             DA_GROUP(vb, 3, p1, 8, sa);
;             l += sa + sb;
;             pw[0] = DA_PACK8(p0, 0); pw[1] = DA_PACK8(p0, 8); pw[2] = DA_PACK8(p1, 0); pw[3] = DA_PACK8(p1, 8);
;             ks_cur = (ks_cur == 2) ? 0 : ks_cur + 1; ks_n2 = (ks_n2 == 2) ? 0 : ks_n2 + 1;
.Lda_mid_bar:
	s_waitcnt lgkmcnt(0)
	s_barrier
	v_mfma_f32_32x32x16_bf16 v[64:79], v[140:143], v[160:163], v[64:79]
	v_exp_f32_e32 v0, v96
	v_exp_f32_e32 v15, v97
	s_add_i32 s0, s46, 1
	v_add_f32_e32 v96, v15, v0
	s_cmp_lg_u32 s46, 2
	s_cselect_b32 s46, s0, 0
	v_lshl_add_u32 v252, s46, 14, v216
	v_add_u32_e32 v253, v252, v191
	v_add_u32_e32 v252, v252, v218
	v_mfma_f32_32x32x16_bf16 v[64:79], v[136:139], v[156:159], v[64:79]
	v_exp_f32_e32 v156, v98
	v_exp_f32_e32 v157, v99
	v_add_f32_e32 v96, v156, v96
	v_add_f32_e32 v96, v157, v96
	ds_read_b128 v[172:175], v253
	ds_read_b128 v[176:179], v252
	ds_read_b128 v[168:171], v253 offset:4096
	ds_read_b128 v[164:167], v252 offset:4096
	v_mfma_f32_32x32x16_bf16 v[64:79], v[116:119], v[152:155], v[64:79]
	v_exp_f32_e32 v158, v100
	v_exp_f32_e32 v159, v101
	v_add_f32_e32 v96, v158, v96
	v_add_f32_e32 v96, v159, v96
	s_add_i32 s0, s47, 1
	s_cmp_lg_u32 s47, 2
	s_cselect_b32 s47, s0, 0
	s_lshl_b32 s0, s47, 14
	s_add_i32 s19, s3, s0
	s_and_b32 s21, s16, 0xc000
	v_mfma_f32_32x32x16_bf16 v[64:79], v[112:115], v[148:151], v[64:79]
	v_exp_f32_e32 v160, v102
	v_exp_f32_e32 v161, v103
	v_add_f32_e32 v162, v160, v96
	ds_read_b64_tr_b16 v[96:97], v234 offset:8192
	ds_read_b64_tr_b16 v[98:99], v234 offset:8704
	ds_read_b64_tr_b16 v[100:101], v234 offset:9216
	ds_read_b64_tr_b16 v[102:103], v234 offset:9728
	ds_read_b64_tr_b16 v[148:149], v234 offset:10240
	ds_read_b64_tr_b16 v[150:151], v234 offset:10752
	ds_read_b64_tr_b16 v[152:153], v234 offset:11264
	ds_read_b64_tr_b16 v[154:155], v234 offset:11776
	v_add_f32_e32 v162, v161, v162
	v_mfma_f32_32x32x16_bf16 v[48:63], v[140:143], v[144:147], v[48:63]
	v_exp_f32_e32 v144, v104
	v_exp_f32_e32 v145, v105
	v_add_f32_e32 v104, v144, v162
	v_add_f32_e32 v104, v145, v104
	s_add_u32 s16, s16, 0x4000
	s_addc_u32 s17, s17, 0
	s_add_i32 s0, s16, 0x4000
	s_and_b32 s0, s0, 0xc000
	s_add_i32 s0, s3, s0
	s_add_i32 s32, s0, 0xc000
	s_add_i32 s45, s45, 1
	s_add_i32 s44, s44, 64
	v_mfma_f32_32x32x16_bf16 v[48:63], v[136:139], v[10:13], v[48:63]
	v_exp_f32_e32 v146, v106
	v_exp_f32_e32 v147, v107
	v_add_f32_e32 v10, v146, v104
	v_add_f32_e32 v10, v147, v10
	s_add_i32 s0, s40, s44
	s_cmpk_gt_i32 s0, 0x9e
	s_cselect_b32 s20, 2, 1
	v_mfma_f32_32x32x16_bf16 v[48:63], v[116:119], v[6:9], v[48:63]
	v_exp_f32_e32 v184, v108
	v_exp_f32_e32 v185, v109
	v_add_f32_e32 v6, v184, v10
	v_add_f32_e32 v6, v185, v6
	s_cmpk_lt_i32 s0, 0xff42
	s_cselect_b64 s[0:1], -1, 0
	s_cmp_lg_u64 s[0:1], 0
	s_subb_u32 s51, s20, 0
	v_mfma_f32_32x32x16_bf16 v[48:63], v[112:115], v[2:5], v[48:63]
	v_exp_f32_e32 v209, v110
	v_exp_f32_e32 v235, v111
	v_add_f32_e32 v162, v209, v6
	ds_read_b64_tr_b16 v[2:3], v234 offset:12288
	ds_read_b64_tr_b16 v[4:5], v234 offset:12800
	ds_read_b64_tr_b16 v[6:7], v234 offset:13312
	ds_read_b64_tr_b16 v[8:9], v234 offset:13824
	ds_read_b64_tr_b16 v[10:11], v234 offset:14336
	ds_read_b64_tr_b16 v[12:13], v234 offset:14848
	ds_read_b64_tr_b16 v[104:105], v234 offset:15360
	ds_read_b64_tr_b16 v[106:107], v234 offset:15872
	s_waitcnt lgkmcnt(8)
	v_add_f32_e32 v162, v235, v162
	v_mfma_f32_32x32x16_bf16 v[32:47], v[140:143], v[96:99], v[32:47]
	v_exp_f32_e32 v80, v80
	v_exp_f32_e32 v81, v81
	v_add_f32_e32 v96, v80, v162
	v_add_f32_e32 v96, v81, v96
	v_mfma_f32_32x32x16_bf16 v[32:47], v[136:139], v[100:103], v[32:47]
	v_exp_f32_e32 v82, v82
	v_exp_f32_e32 v83, v83
	v_add_f32_e32 v96, v82, v96
	v_add_f32_e32 v96, v83, v96
	v_mfma_f32_32x32x16_bf16 v[32:47], v[116:119], v[148:151], v[32:47]
	v_exp_f32_e32 v84, v84
	v_exp_f32_e32 v85, v85
	v_add_f32_e32 v96, v84, v96
	v_add_f32_e32 v96, v85, v96
	v_mfma_f32_32x32x16_bf16 v[32:47], v[112:115], v[152:155], v[32:47]
	v_exp_f32_e32 v86, v86
	v_exp_f32_e32 v87, v87
	v_add_f32_e32 v96, v86, v96
	v_add_f32_e32 v96, v87, v96
	s_waitcnt lgkmcnt(0)
	v_mfma_f32_32x32x16_bf16 v[16:31], v[140:143], v[2:5], v[16:31]
	v_exp_f32_e32 v2, v88
	v_exp_f32_e32 v3, v89
	v_add_f32_e32 v4, v2, v96
	v_add_f32_e32 v4, v3, v4
	v_mfma_f32_32x32x16_bf16 v[16:31], v[136:139], v[6:9], v[16:31]
	v_exp_f32_e32 v5, v90
	v_exp_f32_e32 v6, v91
	v_add_f32_e32 v4, v5, v4
	v_add_f32_e32 v4, v6, v4
	v_mfma_f32_32x32x16_bf16 v[16:31], v[116:119], v[10:13], v[16:31]
	v_exp_f32_e32 v7, v92
	v_exp_f32_e32 v8, v93
	v_add_f32_e32 v4, v7, v4
	v_add_f32_e32 v4, v8, v4
	v_mfma_f32_32x32x16_bf16 v[16:31], v[112:115], v[104:107], v[16:31]
	v_exp_f32_e32 v9, v94
	v_exp_f32_e32 v10, v95
	v_add_f32_e32 v4, v9, v4
	v_add_f32_e32 v4, v10, v4
	v_add_f32_e32 v229, v229, v4
	s_cmp_eq_u32 s41, s44
	s_cbranch_scc1 .LBB0_228

; __device__ __forceinline__ void da_phase(LAS unsigned char* lds, const bf16* Q, const bf16* Kb, const bf16* Vb, bf16* O, const float* lq1, const float* lk1, const float* lq2, const float* lk2,
;                                          const float* t5, int G, int wave, int lane, int tid) {
;     ...
;             if (t + 2 < NT) DA_DMA_K(t + 2, ks_n2);
;     ...
;             if (t + 2 < NT) DA_DMA_V(t + 2, (t + 2) & 3);
.LBB0_215:
	v_mfma_f32_32x32x16_bf16 v[96:111], v[172:175], v[120:123], v[236:251]
	ds_read_b128 v[172:175], v252 offset:2048
	v_cvt_pk_bf16_f32 v140, v0, v15
	v_cvt_pk_bf16_f32 v141, v156, v157
	v_cvt_pk_bf16_f32 v142, v158, v159
	v_cvt_pk_bf16_f32 v143, v160, v161
	v_mfma_f32_32x32x16_bf16 v[96:111], v[176:179], v[124:127], v[96:111]
	ds_read_b128 v[176:179], v253 offset:2048
	v_cvt_pk_bf16_f32 v136, v144, v145
	v_cvt_pk_bf16_f32 v137, v146, v147
	v_cvt_pk_bf16_f32 v138, v184, v185
	v_cvt_pk_bf16_f32 v139, v209, v235
	v_mfma_f32_32x32x16_bf16 v[96:111], v[168:171], v[128:131], v[96:111]
	ds_read_b128 v[168:171], v253 offset:6144
	v_cvt_pk_bf16_f32 v116, v80, v81
	v_cvt_pk_bf16_f32 v117, v82, v83
	v_cvt_pk_bf16_f32 v118, v84, v85
	v_cvt_pk_bf16_f32 v119, v86, v87
	v_mfma_f32_32x32x16_bf16 v[96:111], v[164:167], v[132:135], v[96:111]
	ds_read_b128 v[164:167], v252 offset:6144
	v_cvt_pk_bf16_f32 v112, v2, v3
	v_cvt_pk_bf16_f32 v113, v5, v6
	v_cvt_pk_bf16_f32 v114, v7, v8
	v_cvt_pk_bf16_f32 v115, v9, v10
	s_cmp_ge_u32 s45, s39
	s_cbranch_scc1 .LBB0_217
	s_mov_b32 m0, s19
	s_add_u32 s68, s68, 0x4000
	s_addc_u32 s69, s69, 0
	global_load_lds_dwordx4 v194, s[68:69]
	s_add_i32 m0, m0, 0x400
	s_nop 0
	global_load_lds_dwordx4 v204, s[68:69]
.LBB0_217:
	s_waitcnt lgkmcnt(0)
	v_mfma_f32_32x32x16_bf16 v[80:95], v[176:179], v[120:123], v[236:251]
	ds_read_b64_tr_b16 v[160:161], v234 offset:0
	ds_read_b64_tr_b16 v[162:163], v234 offset:512
	ds_read_b64_tr_b16 v[156:157], v234 offset:1024
	ds_read_b64_tr_b16 v[158:159], v234 offset:1536
	v_max3_f32 v0, v96, v97, v98
	v_max3_f32 v0, v0, v99, v100
	v_mfma_f32_32x32x16_bf16 v[80:95], v[172:175], v[124:127], v[80:95]
	ds_read_b64_tr_b16 v[152:153], v234 offset:2048
	ds_read_b64_tr_b16 v[154:155], v234 offset:2560
	ds_read_b64_tr_b16 v[148:149], v234 offset:3072
	ds_read_b64_tr_b16 v[150:151], v234 offset:3584
	v_max3_f32 v0, v0, v101, v102
	v_max3_f32 v0, v0, v103, v104
	v_mfma_f32_32x32x16_bf16 v[80:95], v[168:171], v[128:131], v[80:95]
	ds_read_b64_tr_b16 v[144:145], v234 offset:4096
	ds_read_b64_tr_b16 v[146:147], v234 offset:4608
	ds_read_b64_tr_b16 v[10:11], v234 offset:5120
	ds_read_b64_tr_b16 v[12:13], v234 offset:5632
	v_max3_f32 v0, v0, v105, v106
	v_max3_f32 v0, v0, v107, v108
	v_mfma_f32_32x32x16_bf16 v[80:95], v[164:167], v[132:135], v[80:95]
	ds_read_b64_tr_b16 v[6:7], v234 offset:6144
	ds_read_b64_tr_b16 v[8:9], v234 offset:6656
	ds_read_b64_tr_b16 v[2:3], v234 offset:7168
	ds_read_b64_tr_b16 v[4:5], v234 offset:7680
	v_max_f32_e32 v0, v0, v0
	v_max_f32_e32 v15, v109, v109
	v_max_f32_e32 v0, v0, v15
	v_max3_f32 v0, v0, v110, v111
	s_cmp_gt_u32 s45, s39
	s_cbranch_scc1 .Lda_vskip
	s_mov_b32 m0, s32
	s_add_u32 s74, s74, 0x4000
	s_addc_u32 s75, s75, 0
	global_load_lds_dwordx4 v196, s[74:75]
	s_add_i32 m0, m0, 0x400
	s_nop 0
	global_load_lds_dwordx4 v205, s[74:75]
